# lora-up GEMM epilogue: the four bias quads are loaded once per tile instead of in each of the 16 pieces (removes 15 load+store-ack waits per tile)
# baseline (speedup 1.0000x reference)
; __device__ __forceinline__ unsigned cvt_pk_bf16(float lo, float hi) { unsigned r; asm volatile("v_cvt_pk_bf16_f32 %0, %1, %2" : "=v"(r) : "v"(lo), "v"(hi)); return r; }
;     __device__ __forceinline__ void operator()(const f32x4 (&acc)[2][2][4][2], const Unit& u, int wr, int wc, int fr, int fq) const {
;     ...
;         if (ACT == 3) { blk = u.pn >> 2; cb = u.pn * BM + wc * 32 + 8 * fq; }
; #pragma unroll
;         for (int ai = 0; ai < 2; ++ai)
; #pragma unroll
;             for (int m = 0; m < 4; ++m) { bf16_t* rowp = base + (size_t)(row0 + ai * HALF + m * 16) * ldc + col0;
; #pragma unroll
;                 for (int bj = 0; bj < 2; ++bj) { f32x4 v0 = acc[ai][bj][m][0], v1 = acc[ai][bj][m][1];
;                     if (ACT == 2) {
; #pragma unroll
;                         for (int e = 0; e < 4; ++e) { float a = fmaxf(v0[e], 0.f), b = fmaxf(v1[e], 0.f); v0[e] = a * a; v1[e] = b * b; } }
;                     if (ACT == 3) {
;                         v0 = v0 + *(const f32x4*)(zb + cb + bj * HALF); v1 = v1 + *(const f32x4*)(zb + cb + bj * HALF + 4);
;                         if (blk < 4) {
; #pragma unroll
;                             for (int e = 0; e < 4; ++e) { float s0 = 1.f / (1.f + __expf(-v0[e])), s1 = 1.f / (1.f + __expf(-v1[e]));
;                                 if (blk < 2) { s0 = 1.f - __expf(-0.60653066f * s0); s1 = 1.f - __expf(-0.60653066f * s1); }
;                                 v0[e] = s0; v1[e] = s1; } } }
;                     v0 = v0 * sc; v1 = v1 * sc; u32x4 w; w.x = cvt_pk_bf16(v0[0], v0[1]); w.y = cvt_pk_bf16(v0[2], v0[3]); w.z = cvt_pk_bf16(v1[0], v1[1]); w.w = cvt_pk_bf16(v1[2], v1[3]);
;                     *(u32x4*)(rowp + bj * HALF) = w; } }
.LBB0_563:
	v_lshl_or_b32 v142, s8, 8, v150
	v_ashrrev_i32_e32 v143, 31, v142
	v_lshl_add_u64 v[140:141], v[142:143], 2, s[12:13]
	global_load_dwordx4 v[202:205], v[140:141], off
	global_load_dwordx4 v[206:209], v[140:141], off offset:16
	global_load_dwordx4 v[210:213], v[140:141], off offset:512
	global_load_dwordx4 v[246:249], v[140:141], off offset:528
	s_ashr_i32 s10, s8, 2
	s_cmp_lt_i32 s10, 4
	s_cselect_b64 s[8:9], -1, 0
	s_cmp_lt_i32 s10, 2
	s_cselect_b64 s[0:1], -1, 0
	s_cmp_gt_i32 s10, 3
	s_waitcnt vmcnt(0)
	v_mov_b32_e32 v154, v206
	v_mov_b32_e32 v155, v207
	v_mov_b32_e32 v156, v208
	v_mov_b32_e32 v157, v209
	v_mov_b32_e32 v158, v202
	v_mov_b32_e32 v159, v203
	v_mov_b32_e32 v160, v204
	v_mov_b32_e32 v161, v205
	v_pk_add_f32 v[126:127], v[126:127], v[156:157]
	v_pk_add_f32 v[146:147], v[120:121], v[158:159]
	v_cndmask_b32_e64 v120, 0, 1, s[0:1]
	v_pk_add_f32 v[144:145], v[122:123], v[160:161]
	v_pk_add_f32 v[124:125], v[124:125], v[154:155]
	v_cmp_ne_u32_e64 s[40:41], 1, v120
	s_cbranch_scc1 .LBB0_573
	v_mul_f32_e32 v120, 0xbfb8aa3b, v146
	v_mul_f32_e32 v121, 0xbfb8aa3b, v124
	v_exp_f32_e32 v120, v120
	v_exp_f32_e32 v121, v121
	s_nop 0
	v_pk_add_f32 v[120:121], v[120:121], 1.0 op_sel_hi:[1,0]
	s_nop 0
	v_div_scale_f32 v122, s[0:1], v121, v121, 1.0
	v_rcp_f32_e32 v123, v122
	s_nop 0
	v_fma_f32 v124, -v122, v123, 1.0
	v_fmac_f32_e32 v123, v124, v123
	v_div_scale_f32 v124, vcc, 1.0, v121, 1.0
	v_mul_f32_e32 v146, v124, v123
	v_fma_f32 v154, -v122, v146, v124
	v_fmac_f32_e32 v146, v154, v123
	v_fma_f32 v122, -v122, v146, v124
	v_div_fmas_f32 v122, v122, v123, v146
	v_div_fixup_f32 v121, v122, v121, 1.0
	v_div_scale_f32 v122, s[0:1], v120, v120, 1.0
	v_rcp_f32_e32 v123, v122
	s_nop 0
	v_fma_f32 v124, -v122, v123, 1.0
	v_fmac_f32_e32 v123, v124, v123
	v_div_scale_f32 v124, vcc, 1.0, v120, 1.0
	v_mul_f32_e32 v146, v124, v123
	v_fma_f32 v154, -v122, v146, v124
	v_fmac_f32_e32 v146, v154, v123
	v_fma_f32 v122, -v122, v146, v124
	v_div_fmas_f32 v122, v122, v123, v146
	v_div_fixup_f32 v120, v122, v120, 1.0
	s_and_b64 vcc, exec, s[40:41]
	s_cbranch_vccnz .LBB0_566
	v_mul_f32_e32 v120, 0xbf1b4598, v120
	v_mul_f32_e32 v121, 0xbf1b4598, v121
	v_mul_f32_e32 v120, 0x3fb8aa3b, v120
	v_mul_f32_e32 v121, 0x3fb8aa3b, v121
	v_exp_f32_e32 v120, v120
	v_exp_f32_e32 v121, v121
	s_nop 0
	v_pk_add_f32 v[120:121], v[120:121], 1.0 op_sel_hi:[1,0] neg_lo:[1,0] neg_hi:[1,0]

; __device__ __forceinline__ unsigned cvt_pk_bf16(float lo, float hi) { unsigned r; asm volatile("v_cvt_pk_bf16_f32 %0, %1, %2" : "=v"(r) : "v"(lo), "v"(hi)); return r; }
;     __device__ __forceinline__ void operator()(const f32x4 (&acc)[2][2][4][2], const Unit& u, int wr, int wc, int fr, int fq) const {
;     ...
;             for (int m = 0; m < 4; ++m) { bf16_t* rowp = base + (size_t)(row0 + ai * HALF + m * 16) * ldc + col0;
; #pragma unroll
;                 for (int bj = 0; bj < 2; ++bj) { f32x4 v0 = acc[ai][bj][m][0], v1 = acc[ai][bj][m][1];
;                     if (ACT == 2) {
; #pragma unroll
;                         for (int e = 0; e < 4; ++e) { float a = fmaxf(v0[e], 0.f), b = fmaxf(v1[e], 0.f); v0[e] = a * a; v1[e] = b * b; } }
;                     if (ACT == 3) {
;                         v0 = v0 + *(const f32x4*)(zb + cb + bj * HALF); v1 = v1 + *(const f32x4*)(zb + cb + bj * HALF + 4);
;                         if (blk < 4) {
; #pragma unroll
;                             for (int e = 0; e < 4; ++e) { float s0 = 1.f / (1.f + __expf(-v0[e])), s1 = 1.f / (1.f + __expf(-v1[e]));
;                                 if (blk < 2) { s0 = 1.f - __expf(-0.60653066f * s0); s1 = 1.f - __expf(-0.60653066f * s1); }
;                                 v0[e] = s0; v1[e] = s1; } } }
;                     v0 = v0 * sc; v1 = v1 * sc; u32x4 w; w.x = cvt_pk_bf16(v0[0], v0[1]); w.y = cvt_pk_bf16(v0[2], v0[3]); w.z = cvt_pk_bf16(v1[0], v1[1]); w.w = cvt_pk_bf16(v1[2], v1[3]);
;                     *(u32x4*)(rowp + bj * HALF) = w; } }
.LBB0_573:
	v_lshl_add_u32 v154, s14, 8, v148
	v_lshl_add_u64 v[120:121], v[142:143], 1, s[4:5]
	v_mad_i64_i32 v[122:123], s[0:1], v154, s35, v[120:121]
	v_cvt_pk_bf16_f32 v142, v146, v147
	v_cvt_pk_bf16_f32 v143, v144, v145
	v_cvt_pk_bf16_f32 v144, v124, v125
	v_cvt_pk_bf16_f32 v145, v126, v127
	global_store_dwordx4 v[122:123], v[142:145], off
	s_nop 1
	v_mov_b32_e32 v142, v210
	v_mov_b32_e32 v143, v211
	v_mov_b32_e32 v144, v212
	v_mov_b32_e32 v145, v213
	s_nop 0
	v_mov_b32_e32 v156, v246
	v_mov_b32_e32 v157, v247
	v_mov_b32_e32 v158, v248
	v_mov_b32_e32 v159, v249
	v_cndmask_b32_e64 v124, 0, 1, s[8:9]
	v_cmp_ne_u32_e64 s[42:43], 1, v124
	s_andn2_b64 vcc, exec, s[8:9]
	v_pk_add_f32 v[124:125], v[114:115], v[144:145]
	v_pk_add_f32 v[142:143], v[112:113], v[142:143]
	v_pk_add_f32 v[114:115], v[118:119], v[158:159]
	v_pk_add_f32 v[126:127], v[116:117], v[156:157]
	s_cbranch_vccnz .LBB0_583
	v_mul_f32_e32 v112, 0xbfb8aa3b, v142
	v_mul_f32_e32 v113, 0xbfb8aa3b, v126
	v_exp_f32_e32 v112, v112
	v_exp_f32_e32 v113, v113
	s_nop 0
	v_pk_add_f32 v[112:113], v[112:113], 1.0 op_sel_hi:[1,0]
	s_nop 0
	v_div_scale_f32 v116, s[0:1], v113, v113, 1.0
	v_rcp_f32_e32 v117, v116
	s_nop 0
	v_fma_f32 v118, -v116, v117, 1.0
	v_fmac_f32_e32 v117, v118, v117
	v_div_scale_f32 v118, vcc, 1.0, v113, 1.0
	v_mul_f32_e32 v119, v118, v117
	v_fma_f32 v126, -v116, v119, v118
	v_fmac_f32_e32 v119, v126, v117
	v_fma_f32 v116, -v116, v119, v118
	v_div_fmas_f32 v116, v116, v117, v119
	v_div_fixup_f32 v113, v116, v113, 1.0
	v_div_scale_f32 v116, s[0:1], v112, v112, 1.0
	v_rcp_f32_e32 v117, v116
	s_nop 0
	v_fma_f32 v118, -v116, v117, 1.0
	v_fmac_f32_e32 v117, v118, v117
	v_div_scale_f32 v118, vcc, 1.0, v112, 1.0
	v_mul_f32_e32 v119, v118, v117
	v_fma_f32 v126, -v116, v119, v118
	v_fmac_f32_e32 v119, v126, v117
	v_fma_f32 v116, -v116, v119, v118
	v_div_fmas_f32 v116, v116, v117, v119
	v_div_fixup_f32 v112, v116, v112, 1.0
	s_and_b64 vcc, exec, s[40:41]
	s_cbranch_vccnz .LBB0_576
	v_mul_f32_e32 v112, 0xbf1b4598, v112
	v_mul_f32_e32 v113, 0xbf1b4598, v113
	v_mul_f32_e32 v112, 0x3fb8aa3b, v112
	v_mul_f32_e32 v113, 0x3fb8aa3b, v113
	v_exp_f32_e32 v112, v112
	v_exp_f32_e32 v113, v113
	s_nop 0
	v_pk_add_f32 v[112:113], v[112:113], 1.0 op_sel_hi:[1,0] neg_lo:[1,0] neg_hi:[1,0]

; __device__ __forceinline__ unsigned cvt_pk_bf16(float lo, float hi) { unsigned r; asm volatile("v_cvt_pk_bf16_f32 %0, %1, %2" : "=v"(r) : "v"(lo), "v"(hi)); return r; }
;     __device__ __forceinline__ void operator()(const f32x4 (&acc)[2][2][4][2], const Unit& u, int wr, int wc, int fr, int fq) const {
;     ...
;             for (int m = 0; m < 4; ++m) { bf16_t* rowp = base + (size_t)(row0 + ai * HALF + m * 16) * ldc + col0;
; #pragma unroll
;                 for (int bj = 0; bj < 2; ++bj) { f32x4 v0 = acc[ai][bj][m][0], v1 = acc[ai][bj][m][1];
;                     if (ACT == 2) {
; #pragma unroll
;                         for (int e = 0; e < 4; ++e) { float a = fmaxf(v0[e], 0.f), b = fmaxf(v1[e], 0.f); v0[e] = a * a; v1[e] = b * b; } }
;                     if (ACT == 3) {
;                         v0 = v0 + *(const f32x4*)(zb + cb + bj * HALF); v1 = v1 + *(const f32x4*)(zb + cb + bj * HALF + 4);
;                         if (blk < 4) {
; #pragma unroll
;                             for (int e = 0; e < 4; ++e) { float s0 = 1.f / (1.f + __expf(-v0[e])), s1 = 1.f / (1.f + __expf(-v1[e]));
;                                 if (blk < 2) { s0 = 1.f - __expf(-0.60653066f * s0); s1 = 1.f - __expf(-0.60653066f * s1); }
;                                 v0[e] = s0; v1[e] = s1; } } }
;                     v0 = v0 * sc; v1 = v1 * sc; u32x4 w; w.x = cvt_pk_bf16(v0[0], v0[1]); w.y = cvt_pk_bf16(v0[2], v0[3]); w.z = cvt_pk_bf16(v1[0], v1[1]); w.w = cvt_pk_bf16(v1[2], v1[3]);
;                     *(u32x4*)(rowp + bj * HALF) = w; } }
.LBB0_583:
	v_cvt_pk_bf16_f32 v116, v142, v143
	v_cvt_pk_bf16_f32 v117, v124, v125
	v_cvt_pk_bf16_f32 v118, v126, v127
	v_cvt_pk_bf16_f32 v119, v114, v115
	global_store_dwordx4 v[122:123], v[116:119], off offset:256
	s_nop 1
	v_mov_b32_e32 v114, v202
	v_mov_b32_e32 v115, v203
	v_mov_b32_e32 v116, v204
	v_mov_b32_e32 v117, v205
	s_nop 0
	v_mov_b32_e32 v122, v206
	v_mov_b32_e32 v123, v207
	v_mov_b32_e32 v124, v208
	v_mov_b32_e32 v125, v209
	s_and_b64 vcc, exec, s[42:43]
	v_pk_add_f32 v[112:113], v[106:107], v[116:117]
	v_pk_add_f32 v[116:117], v[104:105], v[114:115]
	v_pk_add_f32 v[106:107], v[110:111], v[124:125]
	v_pk_add_f32 v[114:115], v[108:109], v[122:123]
	s_cbranch_vccnz .LBB0_593
	v_mul_f32_e32 v104, 0xbfb8aa3b, v116
	v_mul_f32_e32 v105, 0xbfb8aa3b, v114
	v_exp_f32_e32 v104, v104
	v_exp_f32_e32 v105, v105
	s_nop 0
	v_pk_add_f32 v[104:105], v[104:105], 1.0 op_sel_hi:[1,0]
	s_nop 0
	v_div_scale_f32 v108, s[0:1], v105, v105, 1.0
	v_rcp_f32_e32 v109, v108
	s_nop 0
	v_fma_f32 v110, -v108, v109, 1.0
	v_fmac_f32_e32 v109, v110, v109
	v_div_scale_f32 v110, vcc, 1.0, v105, 1.0
	v_mul_f32_e32 v111, v110, v109
	v_fma_f32 v114, -v108, v111, v110
	v_fmac_f32_e32 v111, v114, v109
	v_fma_f32 v108, -v108, v111, v110
	v_div_fmas_f32 v108, v108, v109, v111
	v_div_fixup_f32 v105, v108, v105, 1.0
	v_div_scale_f32 v108, s[0:1], v104, v104, 1.0
	v_rcp_f32_e32 v109, v108
	s_nop 0
	v_fma_f32 v110, -v108, v109, 1.0
	v_fmac_f32_e32 v109, v110, v109
	v_div_scale_f32 v110, vcc, 1.0, v104, 1.0
	v_mul_f32_e32 v111, v110, v109
	v_fma_f32 v114, -v108, v111, v110
	v_fmac_f32_e32 v111, v114, v109
	v_fma_f32 v108, -v108, v111, v110
	v_div_fmas_f32 v108, v108, v109, v111
	v_div_fixup_f32 v104, v108, v104, 1.0
	s_and_b64 vcc, exec, s[40:41]
	s_cbranch_vccnz .LBB0_586
	v_mul_f32_e32 v104, 0xbf1b4598, v104
	v_mul_f32_e32 v105, 0xbf1b4598, v105
	v_mul_f32_e32 v104, 0x3fb8aa3b, v104
	v_mul_f32_e32 v105, 0x3fb8aa3b, v105
	v_exp_f32_e32 v104, v104
	v_exp_f32_e32 v105, v105
	s_nop 0
	v_pk_add_f32 v[104:105], v[104:105], 1.0 op_sel_hi:[1,0] neg_lo:[1,0] neg_hi:[1,0]

; __device__ __forceinline__ unsigned cvt_pk_bf16(float lo, float hi) { unsigned r; asm volatile("v_cvt_pk_bf16_f32 %0, %1, %2" : "=v"(r) : "v"(lo), "v"(hi)); return r; }
;     __device__ __forceinline__ void operator()(const f32x4 (&acc)[2][2][4][2], const Unit& u, int wr, int wc, int fr, int fq) const {
;     ...
;             for (int m = 0; m < 4; ++m) { bf16_t* rowp = base + (size_t)(row0 + ai * HALF + m * 16) * ldc + col0;
; #pragma unroll
;                 for (int bj = 0; bj < 2; ++bj) { f32x4 v0 = acc[ai][bj][m][0], v1 = acc[ai][bj][m][1];
;                     if (ACT == 2) {
; #pragma unroll
;                         for (int e = 0; e < 4; ++e) { float a = fmaxf(v0[e], 0.f), b = fmaxf(v1[e], 0.f); v0[e] = a * a; v1[e] = b * b; } }
;                     if (ACT == 3) {
;                         v0 = v0 + *(const f32x4*)(zb + cb + bj * HALF); v1 = v1 + *(const f32x4*)(zb + cb + bj * HALF + 4);
;                         if (blk < 4) {
; #pragma unroll
;                             for (int e = 0; e < 4; ++e) { float s0 = 1.f / (1.f + __expf(-v0[e])), s1 = 1.f / (1.f + __expf(-v1[e]));
;                                 if (blk < 2) { s0 = 1.f - __expf(-0.60653066f * s0); s1 = 1.f - __expf(-0.60653066f * s1); }
;                                 v0[e] = s0; v1[e] = s1; } } }
;                     v0 = v0 * sc; v1 = v1 * sc; u32x4 w; w.x = cvt_pk_bf16(v0[0], v0[1]); w.y = cvt_pk_bf16(v0[2], v0[3]); w.z = cvt_pk_bf16(v1[0], v1[1]); w.w = cvt_pk_bf16(v1[2], v1[3]);
;                     *(u32x4*)(rowp + bj * HALF) = w; } }
.LBB0_593:
	v_or_b32_e32 v104, 16, v154
	v_mad_i64_i32 v[104:105], s[0:1], v104, s35, v[120:121]
	v_cvt_pk_bf16_f32 v108, v116, v117
	v_cvt_pk_bf16_f32 v109, v112, v113
	v_cvt_pk_bf16_f32 v110, v114, v115
	v_cvt_pk_bf16_f32 v111, v106, v107
	global_store_dwordx4 v[104:105], v[108:111], off
	s_nop 1
	v_mov_b32_e32 v108, v210
	v_mov_b32_e32 v109, v211
	v_mov_b32_e32 v110, v212
	v_mov_b32_e32 v111, v213
	s_nop 0
	v_mov_b32_e32 v112, v246
	v_mov_b32_e32 v113, v247
	v_mov_b32_e32 v114, v248
	v_mov_b32_e32 v115, v249
	s_and_b64 vcc, exec, s[42:43]
	v_pk_add_f32 v[106:107], v[98:99], v[110:111]
	v_pk_add_f32 v[110:111], v[96:97], v[108:109]
	v_pk_add_f32 v[98:99], v[102:103], v[114:115]
	v_pk_add_f32 v[108:109], v[100:101], v[112:113]
	s_cbranch_vccnz .LBB0_603
	v_mul_f32_e32 v96, 0xbfb8aa3b, v110
	v_mul_f32_e32 v97, 0xbfb8aa3b, v108
	v_exp_f32_e32 v96, v96
	v_exp_f32_e32 v97, v97
	s_nop 0
	v_pk_add_f32 v[96:97], v[96:97], 1.0 op_sel_hi:[1,0]
	s_nop 0
	v_div_scale_f32 v100, s[0:1], v97, v97, 1.0
	v_rcp_f32_e32 v101, v100
	s_nop 0
	v_fma_f32 v102, -v100, v101, 1.0
	v_fmac_f32_e32 v101, v102, v101
	v_div_scale_f32 v102, vcc, 1.0, v97, 1.0
	v_mul_f32_e32 v103, v102, v101
	v_fma_f32 v108, -v100, v103, v102
	v_fmac_f32_e32 v103, v108, v101
	v_fma_f32 v100, -v100, v103, v102
	v_div_fmas_f32 v100, v100, v101, v103
	v_div_fixup_f32 v97, v100, v97, 1.0
	v_div_scale_f32 v100, s[0:1], v96, v96, 1.0
	v_rcp_f32_e32 v101, v100
	s_nop 0
	v_fma_f32 v102, -v100, v101, 1.0
	v_fmac_f32_e32 v101, v102, v101
	v_div_scale_f32 v102, vcc, 1.0, v96, 1.0
	v_mul_f32_e32 v103, v102, v101
	v_fma_f32 v108, -v100, v103, v102
	v_fmac_f32_e32 v103, v108, v101
	v_fma_f32 v100, -v100, v103, v102
	v_div_fmas_f32 v100, v100, v101, v103
	v_div_fixup_f32 v96, v100, v96, 1.0
	s_and_b64 vcc, exec, s[40:41]
	s_cbranch_vccnz .LBB0_596
	v_mul_f32_e32 v96, 0xbf1b4598, v96
	v_mul_f32_e32 v97, 0xbf1b4598, v97
	v_mul_f32_e32 v96, 0x3fb8aa3b, v96
	v_mul_f32_e32 v97, 0x3fb8aa3b, v97
	v_exp_f32_e32 v96, v96
	v_exp_f32_e32 v97, v97
	s_nop 0
	v_pk_add_f32 v[96:97], v[96:97], 1.0 op_sel_hi:[1,0] neg_lo:[1,0] neg_hi:[1,0]

; __device__ __forceinline__ unsigned cvt_pk_bf16(float lo, float hi) { unsigned r; asm volatile("v_cvt_pk_bf16_f32 %0, %1, %2" : "=v"(r) : "v"(lo), "v"(hi)); return r; }
;     __device__ __forceinline__ void operator()(const f32x4 (&acc)[2][2][4][2], const Unit& u, int wr, int wc, int fr, int fq) const {
;     ...
;             for (int m = 0; m < 4; ++m) { bf16_t* rowp = base + (size_t)(row0 + ai * HALF + m * 16) * ldc + col0;
; #pragma unroll
;                 for (int bj = 0; bj < 2; ++bj) { f32x4 v0 = acc[ai][bj][m][0], v1 = acc[ai][bj][m][1];
;                     if (ACT == 2) {
; #pragma unroll
;                         for (int e = 0; e < 4; ++e) { float a = fmaxf(v0[e], 0.f), b = fmaxf(v1[e], 0.f); v0[e] = a * a; v1[e] = b * b; } }
;                     if (ACT == 3) {
;                         v0 = v0 + *(const f32x4*)(zb + cb + bj * HALF); v1 = v1 + *(const f32x4*)(zb + cb + bj * HALF + 4);
;                         if (blk < 4) {
; #pragma unroll
;                             for (int e = 0; e < 4; ++e) { float s0 = 1.f / (1.f + __expf(-v0[e])), s1 = 1.f / (1.f + __expf(-v1[e]));
;                                 if (blk < 2) { s0 = 1.f - __expf(-0.60653066f * s0); s1 = 1.f - __expf(-0.60653066f * s1); }
;                                 v0[e] = s0; v1[e] = s1; } } }
;                     v0 = v0 * sc; v1 = v1 * sc; u32x4 w; w.x = cvt_pk_bf16(v0[0], v0[1]); w.y = cvt_pk_bf16(v0[2], v0[3]); w.z = cvt_pk_bf16(v1[0], v1[1]); w.w = cvt_pk_bf16(v1[2], v1[3]);
;                     *(u32x4*)(rowp + bj * HALF) = w; } }
.LBB0_603:
	v_cvt_pk_bf16_f32 v100, v110, v111
	v_cvt_pk_bf16_f32 v101, v106, v107
	v_cvt_pk_bf16_f32 v102, v108, v109
	v_cvt_pk_bf16_f32 v103, v98, v99
	global_store_dwordx4 v[104:105], v[100:103], off offset:256
	s_nop 1
	v_mov_b32_e32 v98, v202
	v_mov_b32_e32 v99, v203
	v_mov_b32_e32 v100, v204
	v_mov_b32_e32 v101, v205
	s_nop 0
	v_mov_b32_e32 v102, v206
	v_mov_b32_e32 v103, v207
	v_mov_b32_e32 v104, v208
	v_mov_b32_e32 v105, v209
	s_and_b64 vcc, exec, s[42:43]
	v_pk_add_f32 v[96:97], v[90:91], v[100:101]
	v_pk_add_f32 v[100:101], v[88:89], v[98:99]
	v_pk_add_f32 v[90:91], v[94:95], v[104:105]
	v_pk_add_f32 v[98:99], v[92:93], v[102:103]
	s_cbranch_vccnz .LBB0_613
	v_mul_f32_e32 v88, 0xbfb8aa3b, v100
	v_mul_f32_e32 v89, 0xbfb8aa3b, v98
	v_exp_f32_e32 v88, v88
	v_exp_f32_e32 v89, v89
	s_nop 0
	v_pk_add_f32 v[88:89], v[88:89], 1.0 op_sel_hi:[1,0]
	s_nop 0
	v_div_scale_f32 v92, s[0:1], v89, v89, 1.0
	v_rcp_f32_e32 v93, v92
	s_nop 0
	v_fma_f32 v94, -v92, v93, 1.0
	v_fmac_f32_e32 v93, v94, v93
	v_div_scale_f32 v94, vcc, 1.0, v89, 1.0
	v_mul_f32_e32 v95, v94, v93
	v_fma_f32 v98, -v92, v95, v94
	v_fmac_f32_e32 v95, v98, v93
	v_fma_f32 v92, -v92, v95, v94
	v_div_fmas_f32 v92, v92, v93, v95
	v_div_fixup_f32 v89, v92, v89, 1.0
	v_div_scale_f32 v92, s[0:1], v88, v88, 1.0
	v_rcp_f32_e32 v93, v92
	s_nop 0
	v_fma_f32 v94, -v92, v93, 1.0
	v_fmac_f32_e32 v93, v94, v93
	v_div_scale_f32 v94, vcc, 1.0, v88, 1.0
	v_mul_f32_e32 v95, v94, v93
	v_fma_f32 v98, -v92, v95, v94
	v_fmac_f32_e32 v95, v98, v93
	v_fma_f32 v92, -v92, v95, v94
	v_div_fmas_f32 v92, v92, v93, v95
	v_div_fixup_f32 v88, v92, v88, 1.0
	s_and_b64 vcc, exec, s[40:41]
	s_cbranch_vccnz .LBB0_606
	v_mul_f32_e32 v88, 0xbf1b4598, v88
	v_mul_f32_e32 v89, 0xbf1b4598, v89
	v_mul_f32_e32 v88, 0x3fb8aa3b, v88
	v_mul_f32_e32 v89, 0x3fb8aa3b, v89
	v_exp_f32_e32 v88, v88
	v_exp_f32_e32 v89, v89
	s_nop 0
	v_pk_add_f32 v[88:89], v[88:89], 1.0 op_sel_hi:[1,0] neg_lo:[1,0] neg_hi:[1,0]

; __device__ __forceinline__ unsigned cvt_pk_bf16(float lo, float hi) { unsigned r; asm volatile("v_cvt_pk_bf16_f32 %0, %1, %2" : "=v"(r) : "v"(lo), "v"(hi)); return r; }
;     __device__ __forceinline__ void operator()(const f32x4 (&acc)[2][2][4][2], const Unit& u, int wr, int wc, int fr, int fq) const {
;     ...
;             for (int m = 0; m < 4; ++m) { bf16_t* rowp = base + (size_t)(row0 + ai * HALF + m * 16) * ldc + col0;
; #pragma unroll
;                 for (int bj = 0; bj < 2; ++bj) { f32x4 v0 = acc[ai][bj][m][0], v1 = acc[ai][bj][m][1];
;                     if (ACT == 2) {
; #pragma unroll
;                         for (int e = 0; e < 4; ++e) { float a = fmaxf(v0[e], 0.f), b = fmaxf(v1[e], 0.f); v0[e] = a * a; v1[e] = b * b; } }
;                     if (ACT == 3) {
;                         v0 = v0 + *(const f32x4*)(zb + cb + bj * HALF); v1 = v1 + *(const f32x4*)(zb + cb + bj * HALF + 4);
;                         if (blk < 4) {
; #pragma unroll
;                             for (int e = 0; e < 4; ++e) { float s0 = 1.f / (1.f + __expf(-v0[e])), s1 = 1.f / (1.f + __expf(-v1[e]));
;                                 if (blk < 2) { s0 = 1.f - __expf(-0.60653066f * s0); s1 = 1.f - __expf(-0.60653066f * s1); }
;                                 v0[e] = s0; v1[e] = s1; } } }
;                     v0 = v0 * sc; v1 = v1 * sc; u32x4 w; w.x = cvt_pk_bf16(v0[0], v0[1]); w.y = cvt_pk_bf16(v0[2], v0[3]); w.z = cvt_pk_bf16(v1[0], v1[1]); w.w = cvt_pk_bf16(v1[2], v1[3]);
;                     *(u32x4*)(rowp + bj * HALF) = w; } }
.LBB0_613:
	v_or_b32_e32 v88, 32, v154
	v_mad_i64_i32 v[88:89], s[0:1], v88, s35, v[120:121]
	v_cvt_pk_bf16_f32 v92, v100, v101
	v_cvt_pk_bf16_f32 v93, v96, v97
	v_cvt_pk_bf16_f32 v94, v98, v99
	v_cvt_pk_bf16_f32 v95, v90, v91
	global_store_dwordx4 v[88:89], v[92:95], off
	s_nop 1
	v_mov_b32_e32 v92, v210
	v_mov_b32_e32 v93, v211
	v_mov_b32_e32 v94, v212
	v_mov_b32_e32 v95, v213
	s_nop 0
	v_mov_b32_e32 v96, v246
	v_mov_b32_e32 v97, v247
	v_mov_b32_e32 v98, v248
	v_mov_b32_e32 v99, v249
	s_and_b64 vcc, exec, s[42:43]
	v_pk_add_f32 v[90:91], v[82:83], v[94:95]
	v_pk_add_f32 v[94:95], v[80:81], v[92:93]
	v_pk_add_f32 v[82:83], v[86:87], v[98:99]
	v_pk_add_f32 v[92:93], v[84:85], v[96:97]
	s_cbranch_vccnz .LBB0_623
	v_mul_f32_e32 v80, 0xbfb8aa3b, v94
	v_mul_f32_e32 v81, 0xbfb8aa3b, v92
	v_exp_f32_e32 v80, v80
	v_exp_f32_e32 v81, v81
	s_nop 0
	v_pk_add_f32 v[80:81], v[80:81], 1.0 op_sel_hi:[1,0]
	s_nop 0
	v_div_scale_f32 v84, s[0:1], v81, v81, 1.0
	v_rcp_f32_e32 v85, v84
	s_nop 0
	v_fma_f32 v86, -v84, v85, 1.0
	v_fmac_f32_e32 v85, v86, v85
	v_div_scale_f32 v86, vcc, 1.0, v81, 1.0
	v_mul_f32_e32 v87, v86, v85
	v_fma_f32 v92, -v84, v87, v86
	v_fmac_f32_e32 v87, v92, v85
	v_fma_f32 v84, -v84, v87, v86
	v_div_fmas_f32 v84, v84, v85, v87
	v_div_fixup_f32 v81, v84, v81, 1.0
	v_div_scale_f32 v84, s[0:1], v80, v80, 1.0
	v_rcp_f32_e32 v85, v84
	s_nop 0
	v_fma_f32 v86, -v84, v85, 1.0
	v_fmac_f32_e32 v85, v86, v85
	v_div_scale_f32 v86, vcc, 1.0, v80, 1.0
	v_mul_f32_e32 v87, v86, v85
	v_fma_f32 v92, -v84, v87, v86
	v_fmac_f32_e32 v87, v92, v85
	v_fma_f32 v84, -v84, v87, v86
	v_div_fmas_f32 v84, v84, v85, v87
	v_div_fixup_f32 v80, v84, v80, 1.0
	s_and_b64 vcc, exec, s[40:41]
	s_cbranch_vccnz .LBB0_616
	v_mul_f32_e32 v80, 0xbf1b4598, v80
	v_mul_f32_e32 v81, 0xbf1b4598, v81
	v_mul_f32_e32 v80, 0x3fb8aa3b, v80
	v_mul_f32_e32 v81, 0x3fb8aa3b, v81
	v_exp_f32_e32 v80, v80
	v_exp_f32_e32 v81, v81
	s_nop 0
	v_pk_add_f32 v[80:81], v[80:81], 1.0 op_sel_hi:[1,0] neg_lo:[1,0] neg_hi:[1,0]

; __device__ __forceinline__ unsigned cvt_pk_bf16(float lo, float hi) { unsigned r; asm volatile("v_cvt_pk_bf16_f32 %0, %1, %2" : "=v"(r) : "v"(lo), "v"(hi)); return r; }
;     __device__ __forceinline__ void operator()(const f32x4 (&acc)[2][2][4][2], const Unit& u, int wr, int wc, int fr, int fq) const {
;     ...
;             for (int m = 0; m < 4; ++m) { bf16_t* rowp = base + (size_t)(row0 + ai * HALF + m * 16) * ldc + col0;
; #pragma unroll
;                 for (int bj = 0; bj < 2; ++bj) { f32x4 v0 = acc[ai][bj][m][0], v1 = acc[ai][bj][m][1];
;                     if (ACT == 2) {
; #pragma unroll
;                         for (int e = 0; e < 4; ++e) { float a = fmaxf(v0[e], 0.f), b = fmaxf(v1[e], 0.f); v0[e] = a * a; v1[e] = b * b; } }
;                     if (ACT == 3) {
;                         v0 = v0 + *(const f32x4*)(zb + cb + bj * HALF); v1 = v1 + *(const f32x4*)(zb + cb + bj * HALF + 4);
;                         if (blk < 4) {
; #pragma unroll
;                             for (int e = 0; e < 4; ++e) { float s0 = 1.f / (1.f + __expf(-v0[e])), s1 = 1.f / (1.f + __expf(-v1[e]));
;                                 if (blk < 2) { s0 = 1.f - __expf(-0.60653066f * s0); s1 = 1.f - __expf(-0.60653066f * s1); }
;                                 v0[e] = s0; v1[e] = s1; } } }
;                     v0 = v0 * sc; v1 = v1 * sc; u32x4 w; w.x = cvt_pk_bf16(v0[0], v0[1]); w.y = cvt_pk_bf16(v0[2], v0[3]); w.z = cvt_pk_bf16(v1[0], v1[1]); w.w = cvt_pk_bf16(v1[2], v1[3]);
;                     *(u32x4*)(rowp + bj * HALF) = w; } }
.LBB0_623:
	v_cvt_pk_bf16_f32 v84, v94, v95
	v_cvt_pk_bf16_f32 v85, v90, v91
	v_cvt_pk_bf16_f32 v86, v92, v93
	v_cvt_pk_bf16_f32 v87, v82, v83
	global_store_dwordx4 v[88:89], v[84:87], off offset:256
	s_nop 1
	v_mov_b32_e32 v82, v202
	v_mov_b32_e32 v83, v203
	v_mov_b32_e32 v84, v204
	v_mov_b32_e32 v85, v205
	s_nop 0
	v_mov_b32_e32 v86, v206
	v_mov_b32_e32 v87, v207
	v_mov_b32_e32 v88, v208
	v_mov_b32_e32 v89, v209
	s_and_b64 vcc, exec, s[42:43]
	v_pk_add_f32 v[80:81], v[74:75], v[84:85]
	v_pk_add_f32 v[84:85], v[72:73], v[82:83]
	v_pk_add_f32 v[74:75], v[78:79], v[88:89]
	v_pk_add_f32 v[82:83], v[76:77], v[86:87]
	s_cbranch_vccnz .LBB0_633
	v_mul_f32_e32 v72, 0xbfb8aa3b, v84
	v_mul_f32_e32 v73, 0xbfb8aa3b, v82
	v_exp_f32_e32 v72, v72
	v_exp_f32_e32 v73, v73
	s_nop 0
	v_pk_add_f32 v[72:73], v[72:73], 1.0 op_sel_hi:[1,0]
	s_nop 0
	v_div_scale_f32 v76, s[0:1], v73, v73, 1.0
	v_rcp_f32_e32 v77, v76
	s_nop 0
	v_fma_f32 v78, -v76, v77, 1.0
	v_fmac_f32_e32 v77, v78, v77
	v_div_scale_f32 v78, vcc, 1.0, v73, 1.0
	v_mul_f32_e32 v79, v78, v77
	v_fma_f32 v82, -v76, v79, v78
	v_fmac_f32_e32 v79, v82, v77
	v_fma_f32 v76, -v76, v79, v78
	v_div_fmas_f32 v76, v76, v77, v79
	v_div_fixup_f32 v73, v76, v73, 1.0
	v_div_scale_f32 v76, s[0:1], v72, v72, 1.0
	v_rcp_f32_e32 v77, v76
	s_nop 0
	v_fma_f32 v78, -v76, v77, 1.0
	v_fmac_f32_e32 v77, v78, v77
	v_div_scale_f32 v78, vcc, 1.0, v72, 1.0
	v_mul_f32_e32 v79, v78, v77
	v_fma_f32 v82, -v76, v79, v78
	v_fmac_f32_e32 v79, v82, v77
	v_fma_f32 v76, -v76, v79, v78
	v_div_fmas_f32 v76, v76, v77, v79
	v_div_fixup_f32 v72, v76, v72, 1.0
	s_and_b64 vcc, exec, s[40:41]
	s_cbranch_vccnz .LBB0_626
	v_mul_f32_e32 v72, 0xbf1b4598, v72
	v_mul_f32_e32 v73, 0xbf1b4598, v73
	v_mul_f32_e32 v72, 0x3fb8aa3b, v72
	v_mul_f32_e32 v73, 0x3fb8aa3b, v73
	v_exp_f32_e32 v72, v72
	v_exp_f32_e32 v73, v73
	s_nop 0
	v_pk_add_f32 v[72:73], v[72:73], 1.0 op_sel_hi:[1,0] neg_lo:[1,0] neg_hi:[1,0]

; __device__ __forceinline__ unsigned cvt_pk_bf16(float lo, float hi) { unsigned r; asm volatile("v_cvt_pk_bf16_f32 %0, %1, %2" : "=v"(r) : "v"(lo), "v"(hi)); return r; }
;     __device__ __forceinline__ void operator()(const f32x4 (&acc)[2][2][4][2], const Unit& u, int wr, int wc, int fr, int fq) const {
;     ...
;             for (int m = 0; m < 4; ++m) { bf16_t* rowp = base + (size_t)(row0 + ai * HALF + m * 16) * ldc + col0;
; #pragma unroll
;                 for (int bj = 0; bj < 2; ++bj) { f32x4 v0 = acc[ai][bj][m][0], v1 = acc[ai][bj][m][1];
;                     if (ACT == 2) {
; #pragma unroll
;                         for (int e = 0; e < 4; ++e) { float a = fmaxf(v0[e], 0.f), b = fmaxf(v1[e], 0.f); v0[e] = a * a; v1[e] = b * b; } }
;                     if (ACT == 3) {
;                         v0 = v0 + *(const f32x4*)(zb + cb + bj * HALF); v1 = v1 + *(const f32x4*)(zb + cb + bj * HALF + 4);
;                         if (blk < 4) {
; #pragma unroll
;                             for (int e = 0; e < 4; ++e) { float s0 = 1.f / (1.f + __expf(-v0[e])), s1 = 1.f / (1.f + __expf(-v1[e]));
;                                 if (blk < 2) { s0 = 1.f - __expf(-0.60653066f * s0); s1 = 1.f - __expf(-0.60653066f * s1); }
;                                 v0[e] = s0; v1[e] = s1; } } }
;                     v0 = v0 * sc; v1 = v1 * sc; u32x4 w; w.x = cvt_pk_bf16(v0[0], v0[1]); w.y = cvt_pk_bf16(v0[2], v0[3]); w.z = cvt_pk_bf16(v1[0], v1[1]); w.w = cvt_pk_bf16(v1[2], v1[3]);
;                     *(u32x4*)(rowp + bj * HALF) = w; } }
.LBB0_633:
	v_or_b32_e32 v72, 48, v154
	v_mad_i64_i32 v[72:73], s[0:1], v72, s35, v[120:121]
	v_cvt_pk_bf16_f32 v76, v84, v85
	v_cvt_pk_bf16_f32 v77, v80, v81
	v_cvt_pk_bf16_f32 v78, v82, v83
	v_cvt_pk_bf16_f32 v79, v74, v75
	global_store_dwordx4 v[72:73], v[76:79], off
	s_nop 1
	v_mov_b32_e32 v76, v210
	v_mov_b32_e32 v77, v211
	v_mov_b32_e32 v78, v212
	v_mov_b32_e32 v79, v213
	s_nop 0
	v_mov_b32_e32 v80, v246
	v_mov_b32_e32 v81, v247
	v_mov_b32_e32 v82, v248
	v_mov_b32_e32 v83, v249
	s_and_b64 vcc, exec, s[42:43]
	v_pk_add_f32 v[74:75], v[66:67], v[78:79]
	v_pk_add_f32 v[78:79], v[64:65], v[76:77]
	v_pk_add_f32 v[66:67], v[70:71], v[82:83]
	v_pk_add_f32 v[76:77], v[68:69], v[80:81]
	s_cbranch_vccnz .LBB0_643
	v_mul_f32_e32 v64, 0xbfb8aa3b, v78
	v_mul_f32_e32 v65, 0xbfb8aa3b, v76
	v_exp_f32_e32 v64, v64
	v_exp_f32_e32 v65, v65
	s_nop 0
	v_pk_add_f32 v[64:65], v[64:65], 1.0 op_sel_hi:[1,0]
	s_nop 0
	v_div_scale_f32 v68, s[0:1], v65, v65, 1.0
	v_rcp_f32_e32 v69, v68
	s_nop 0
	v_fma_f32 v70, -v68, v69, 1.0
	v_fmac_f32_e32 v69, v70, v69
	v_div_scale_f32 v70, vcc, 1.0, v65, 1.0
	v_mul_f32_e32 v71, v70, v69
	v_fma_f32 v76, -v68, v71, v70
	v_fmac_f32_e32 v71, v76, v69
	v_fma_f32 v68, -v68, v71, v70
	v_div_fmas_f32 v68, v68, v69, v71
	v_div_fixup_f32 v65, v68, v65, 1.0
	v_div_scale_f32 v68, s[0:1], v64, v64, 1.0
	v_rcp_f32_e32 v69, v68
	s_nop 0
	v_fma_f32 v70, -v68, v69, 1.0
	v_fmac_f32_e32 v69, v70, v69
	v_div_scale_f32 v70, vcc, 1.0, v64, 1.0
	v_mul_f32_e32 v71, v70, v69
	v_fma_f32 v76, -v68, v71, v70
	v_fmac_f32_e32 v71, v76, v69
	v_fma_f32 v68, -v68, v71, v70
	v_div_fmas_f32 v68, v68, v69, v71
	v_div_fixup_f32 v64, v68, v64, 1.0
	s_and_b64 vcc, exec, s[40:41]
	s_cbranch_vccnz .LBB0_636
	v_mul_f32_e32 v64, 0xbf1b4598, v64
	v_mul_f32_e32 v65, 0xbf1b4598, v65
	v_mul_f32_e32 v64, 0x3fb8aa3b, v64
	v_mul_f32_e32 v65, 0x3fb8aa3b, v65
	v_exp_f32_e32 v64, v64
	v_exp_f32_e32 v65, v65
	s_nop 0
	v_pk_add_f32 v[64:65], v[64:65], 1.0 op_sel_hi:[1,0] neg_lo:[1,0] neg_hi:[1,0]

; __device__ __forceinline__ unsigned cvt_pk_bf16(float lo, float hi) { unsigned r; asm volatile("v_cvt_pk_bf16_f32 %0, %1, %2" : "=v"(r) : "v"(lo), "v"(hi)); return r; }
;     __device__ __forceinline__ void operator()(const f32x4 (&acc)[2][2][4][2], const Unit& u, int wr, int wc, int fr, int fq) const {
;     ...
;             for (int m = 0; m < 4; ++m) { bf16_t* rowp = base + (size_t)(row0 + ai * HALF + m * 16) * ldc + col0;
; #pragma unroll
;                 for (int bj = 0; bj < 2; ++bj) { f32x4 v0 = acc[ai][bj][m][0], v1 = acc[ai][bj][m][1];
;                     if (ACT == 2) {
; #pragma unroll
;                         for (int e = 0; e < 4; ++e) { float a = fmaxf(v0[e], 0.f), b = fmaxf(v1[e], 0.f); v0[e] = a * a; v1[e] = b * b; } }
;                     if (ACT == 3) {
;                         v0 = v0 + *(const f32x4*)(zb + cb + bj * HALF); v1 = v1 + *(const f32x4*)(zb + cb + bj * HALF + 4);
;                         if (blk < 4) {
; #pragma unroll
;                             for (int e = 0; e < 4; ++e) { float s0 = 1.f / (1.f + __expf(-v0[e])), s1 = 1.f / (1.f + __expf(-v1[e]));
;                                 if (blk < 2) { s0 = 1.f - __expf(-0.60653066f * s0); s1 = 1.f - __expf(-0.60653066f * s1); }
;                                 v0[e] = s0; v1[e] = s1; } } }
;                     v0 = v0 * sc; v1 = v1 * sc; u32x4 w; w.x = cvt_pk_bf16(v0[0], v0[1]); w.y = cvt_pk_bf16(v0[2], v0[3]); w.z = cvt_pk_bf16(v1[0], v1[1]); w.w = cvt_pk_bf16(v1[2], v1[3]);
;                     *(u32x4*)(rowp + bj * HALF) = w; } }
.LBB0_643:
	v_cvt_pk_bf16_f32 v68, v78, v79
	v_cvt_pk_bf16_f32 v69, v74, v75
	v_cvt_pk_bf16_f32 v70, v76, v77
	v_cvt_pk_bf16_f32 v71, v66, v67
	global_store_dwordx4 v[72:73], v[68:71], off offset:256
	s_nop 1
	v_mov_b32_e32 v66, v202
	v_mov_b32_e32 v67, v203
	v_mov_b32_e32 v68, v204
	v_mov_b32_e32 v69, v205
	s_nop 0
	v_mov_b32_e32 v70, v206
	v_mov_b32_e32 v71, v207
	v_mov_b32_e32 v72, v208
	v_mov_b32_e32 v73, v209
	s_and_b64 vcc, exec, s[42:43]
	v_pk_add_f32 v[64:65], v[58:59], v[68:69]
	v_pk_add_f32 v[68:69], v[56:57], v[66:67]
	v_pk_add_f32 v[58:59], v[62:63], v[72:73]
	v_pk_add_f32 v[66:67], v[60:61], v[70:71]
	s_cbranch_vccnz .LBB0_653
	v_mul_f32_e32 v56, 0xbfb8aa3b, v68
	v_mul_f32_e32 v57, 0xbfb8aa3b, v66
	v_exp_f32_e32 v56, v56
	v_exp_f32_e32 v57, v57
	s_nop 0
	v_pk_add_f32 v[56:57], v[56:57], 1.0 op_sel_hi:[1,0]
	s_nop 0
	v_div_scale_f32 v60, s[0:1], v57, v57, 1.0
	v_rcp_f32_e32 v61, v60
	s_nop 0
	v_fma_f32 v62, -v60, v61, 1.0
	v_fmac_f32_e32 v61, v62, v61
	v_div_scale_f32 v62, vcc, 1.0, v57, 1.0
	v_mul_f32_e32 v63, v62, v61
	v_fma_f32 v66, -v60, v63, v62
	v_fmac_f32_e32 v63, v66, v61
	v_fma_f32 v60, -v60, v63, v62
	v_div_fmas_f32 v60, v60, v61, v63
	v_div_fixup_f32 v57, v60, v57, 1.0
	v_div_scale_f32 v60, s[0:1], v56, v56, 1.0
	v_rcp_f32_e32 v61, v60
	s_nop 0
	v_fma_f32 v62, -v60, v61, 1.0
	v_fmac_f32_e32 v61, v62, v61
	v_div_scale_f32 v62, vcc, 1.0, v56, 1.0
	v_mul_f32_e32 v63, v62, v61
	v_fma_f32 v66, -v60, v63, v62
	v_fmac_f32_e32 v63, v66, v61
	v_fma_f32 v60, -v60, v63, v62
	v_div_fmas_f32 v60, v60, v61, v63
	v_div_fixup_f32 v56, v60, v56, 1.0
	s_and_b64 vcc, exec, s[40:41]
	s_cbranch_vccnz .LBB0_646
	v_mul_f32_e32 v56, 0xbf1b4598, v56
	v_mul_f32_e32 v57, 0xbf1b4598, v57
	v_mul_f32_e32 v56, 0x3fb8aa3b, v56
	v_mul_f32_e32 v57, 0x3fb8aa3b, v57
	v_exp_f32_e32 v56, v56
	v_exp_f32_e32 v57, v57
	s_nop 0
	v_pk_add_f32 v[56:57], v[56:57], 1.0 op_sel_hi:[1,0] neg_lo:[1,0] neg_hi:[1,0]

; __device__ __forceinline__ unsigned cvt_pk_bf16(float lo, float hi) { unsigned r; asm volatile("v_cvt_pk_bf16_f32 %0, %1, %2" : "=v"(r) : "v"(lo), "v"(hi)); return r; }
;     __device__ __forceinline__ void operator()(const f32x4 (&acc)[2][2][4][2], const Unit& u, int wr, int wc, int fr, int fq) const {
;     ...
;             for (int m = 0; m < 4; ++m) { bf16_t* rowp = base + (size_t)(row0 + ai * HALF + m * 16) * ldc + col0;
; #pragma unroll
;                 for (int bj = 0; bj < 2; ++bj) { f32x4 v0 = acc[ai][bj][m][0], v1 = acc[ai][bj][m][1];
;                     if (ACT == 2) {
; #pragma unroll
;                         for (int e = 0; e < 4; ++e) { float a = fmaxf(v0[e], 0.f), b = fmaxf(v1[e], 0.f); v0[e] = a * a; v1[e] = b * b; } }
;                     if (ACT == 3) {
;                         v0 = v0 + *(const f32x4*)(zb + cb + bj * HALF); v1 = v1 + *(const f32x4*)(zb + cb + bj * HALF + 4);
;                         if (blk < 4) {
; #pragma unroll
;                             for (int e = 0; e < 4; ++e) { float s0 = 1.f / (1.f + __expf(-v0[e])), s1 = 1.f / (1.f + __expf(-v1[e]));
;                                 if (blk < 2) { s0 = 1.f - __expf(-0.60653066f * s0); s1 = 1.f - __expf(-0.60653066f * s1); }
;                                 v0[e] = s0; v1[e] = s1; } } }
;                     v0 = v0 * sc; v1 = v1 * sc; u32x4 w; w.x = cvt_pk_bf16(v0[0], v0[1]); w.y = cvt_pk_bf16(v0[2], v0[3]); w.z = cvt_pk_bf16(v1[0], v1[1]); w.w = cvt_pk_bf16(v1[2], v1[3]);
;                     *(u32x4*)(rowp + bj * HALF) = w; } }
.LBB0_653:
	v_add_u32_e32 v56, 0x80, v154
	v_mad_i64_i32 v[56:57], s[0:1], v56, s35, v[120:121]
	v_cvt_pk_bf16_f32 v60, v68, v69
	v_cvt_pk_bf16_f32 v61, v64, v65
	v_cvt_pk_bf16_f32 v62, v66, v67
	v_cvt_pk_bf16_f32 v63, v58, v59
	global_store_dwordx4 v[56:57], v[60:63], off
	s_nop 1
	v_mov_b32_e32 v60, v210
	v_mov_b32_e32 v61, v211
	v_mov_b32_e32 v62, v212
	v_mov_b32_e32 v63, v213
	s_nop 0
	v_mov_b32_e32 v64, v246
	v_mov_b32_e32 v65, v247
	v_mov_b32_e32 v66, v248
	v_mov_b32_e32 v67, v249
	s_and_b64 vcc, exec, s[42:43]
	v_pk_add_f32 v[58:59], v[50:51], v[62:63]
	v_pk_add_f32 v[62:63], v[48:49], v[60:61]
	v_pk_add_f32 v[50:51], v[54:55], v[66:67]
	v_pk_add_f32 v[60:61], v[52:53], v[64:65]
	s_cbranch_vccnz .LBB0_663
	v_mul_f32_e32 v48, 0xbfb8aa3b, v62
	v_mul_f32_e32 v49, 0xbfb8aa3b, v60
	v_exp_f32_e32 v48, v48
	v_exp_f32_e32 v49, v49
	s_nop 0
	v_pk_add_f32 v[48:49], v[48:49], 1.0 op_sel_hi:[1,0]
	s_nop 0
	v_div_scale_f32 v52, s[0:1], v49, v49, 1.0
	v_rcp_f32_e32 v53, v52
	s_nop 0
	v_fma_f32 v54, -v52, v53, 1.0
	v_fmac_f32_e32 v53, v54, v53
	v_div_scale_f32 v54, vcc, 1.0, v49, 1.0
	v_mul_f32_e32 v55, v54, v53
	v_fma_f32 v60, -v52, v55, v54
	v_fmac_f32_e32 v55, v60, v53
	v_fma_f32 v52, -v52, v55, v54
	v_div_fmas_f32 v52, v52, v53, v55
	v_div_fixup_f32 v49, v52, v49, 1.0
	v_div_scale_f32 v52, s[0:1], v48, v48, 1.0
	v_rcp_f32_e32 v53, v52
	s_nop 0
	v_fma_f32 v54, -v52, v53, 1.0
	v_fmac_f32_e32 v53, v54, v53
	v_div_scale_f32 v54, vcc, 1.0, v48, 1.0
	v_mul_f32_e32 v55, v54, v53
	v_fma_f32 v60, -v52, v55, v54
	v_fmac_f32_e32 v55, v60, v53
	v_fma_f32 v52, -v52, v55, v54
	v_div_fmas_f32 v52, v52, v53, v55
	v_div_fixup_f32 v48, v52, v48, 1.0
	s_and_b64 vcc, exec, s[40:41]
	s_cbranch_vccnz .LBB0_656
	v_mul_f32_e32 v48, 0xbf1b4598, v48
	v_mul_f32_e32 v49, 0xbf1b4598, v49
	v_mul_f32_e32 v48, 0x3fb8aa3b, v48
	v_mul_f32_e32 v49, 0x3fb8aa3b, v49
	v_exp_f32_e32 v48, v48
	v_exp_f32_e32 v49, v49
	s_nop 0
	v_pk_add_f32 v[48:49], v[48:49], 1.0 op_sel_hi:[1,0] neg_lo:[1,0] neg_hi:[1,0]

; __device__ __forceinline__ unsigned cvt_pk_bf16(float lo, float hi) { unsigned r; asm volatile("v_cvt_pk_bf16_f32 %0, %1, %2" : "=v"(r) : "v"(lo), "v"(hi)); return r; }
;     __device__ __forceinline__ void operator()(const f32x4 (&acc)[2][2][4][2], const Unit& u, int wr, int wc, int fr, int fq) const {
;     ...
;             for (int m = 0; m < 4; ++m) { bf16_t* rowp = base + (size_t)(row0 + ai * HALF + m * 16) * ldc + col0;
; #pragma unroll
;                 for (int bj = 0; bj < 2; ++bj) { f32x4 v0 = acc[ai][bj][m][0], v1 = acc[ai][bj][m][1];
;                     if (ACT == 2) {
; #pragma unroll
;                         for (int e = 0; e < 4; ++e) { float a = fmaxf(v0[e], 0.f), b = fmaxf(v1[e], 0.f); v0[e] = a * a; v1[e] = b * b; } }
;                     if (ACT == 3) {
;                         v0 = v0 + *(const f32x4*)(zb + cb + bj * HALF); v1 = v1 + *(const f32x4*)(zb + cb + bj * HALF + 4);
;                         if (blk < 4) {
; #pragma unroll
;                             for (int e = 0; e < 4; ++e) { float s0 = 1.f / (1.f + __expf(-v0[e])), s1 = 1.f / (1.f + __expf(-v1[e]));
;                                 if (blk < 2) { s0 = 1.f - __expf(-0.60653066f * s0); s1 = 1.f - __expf(-0.60653066f * s1); }
;                                 v0[e] = s0; v1[e] = s1; } } }
;                     v0 = v0 * sc; v1 = v1 * sc; u32x4 w; w.x = cvt_pk_bf16(v0[0], v0[1]); w.y = cvt_pk_bf16(v0[2], v0[3]); w.z = cvt_pk_bf16(v1[0], v1[1]); w.w = cvt_pk_bf16(v1[2], v1[3]);
;                     *(u32x4*)(rowp + bj * HALF) = w; } }
.LBB0_663:
	v_cvt_pk_bf16_f32 v52, v62, v63
	v_cvt_pk_bf16_f32 v53, v58, v59
	v_cvt_pk_bf16_f32 v54, v60, v61
	v_cvt_pk_bf16_f32 v55, v50, v51
	global_store_dwordx4 v[56:57], v[52:55], off offset:256
	s_nop 1
	v_mov_b32_e32 v50, v202
	v_mov_b32_e32 v51, v203
	v_mov_b32_e32 v52, v204
	v_mov_b32_e32 v53, v205
	s_nop 0
	v_mov_b32_e32 v54, v206
	v_mov_b32_e32 v55, v207
	v_mov_b32_e32 v56, v208
	v_mov_b32_e32 v57, v209
	s_and_b64 vcc, exec, s[42:43]
	v_pk_add_f32 v[48:49], v[42:43], v[52:53]
	v_pk_add_f32 v[52:53], v[40:41], v[50:51]
	v_pk_add_f32 v[42:43], v[46:47], v[56:57]
	v_pk_add_f32 v[50:51], v[44:45], v[54:55]
	s_cbranch_vccnz .LBB0_673
	v_mul_f32_e32 v40, 0xbfb8aa3b, v52
	v_mul_f32_e32 v41, 0xbfb8aa3b, v50
	v_exp_f32_e32 v40, v40
	v_exp_f32_e32 v41, v41
	s_nop 0
	v_pk_add_f32 v[40:41], v[40:41], 1.0 op_sel_hi:[1,0]
	s_nop 0
	v_div_scale_f32 v44, s[0:1], v41, v41, 1.0
	v_rcp_f32_e32 v45, v44
	s_nop 0
	v_fma_f32 v46, -v44, v45, 1.0
	v_fmac_f32_e32 v45, v46, v45
	v_div_scale_f32 v46, vcc, 1.0, v41, 1.0
	v_mul_f32_e32 v47, v46, v45
	v_fma_f32 v50, -v44, v47, v46
	v_fmac_f32_e32 v47, v50, v45
	v_fma_f32 v44, -v44, v47, v46
	v_div_fmas_f32 v44, v44, v45, v47
	v_div_fixup_f32 v41, v44, v41, 1.0
	v_div_scale_f32 v44, s[0:1], v40, v40, 1.0
	v_rcp_f32_e32 v45, v44
	s_nop 0
	v_fma_f32 v46, -v44, v45, 1.0
	v_fmac_f32_e32 v45, v46, v45
	v_div_scale_f32 v46, vcc, 1.0, v40, 1.0
	v_mul_f32_e32 v47, v46, v45
	v_fma_f32 v50, -v44, v47, v46
	v_fmac_f32_e32 v47, v50, v45
	v_fma_f32 v44, -v44, v47, v46
	v_div_fmas_f32 v44, v44, v45, v47
	v_div_fixup_f32 v40, v44, v40, 1.0
	s_and_b64 vcc, exec, s[40:41]
	s_cbranch_vccnz .LBB0_666
	v_mul_f32_e32 v40, 0xbf1b4598, v40
	v_mul_f32_e32 v41, 0xbf1b4598, v41
	v_mul_f32_e32 v40, 0x3fb8aa3b, v40
	v_mul_f32_e32 v41, 0x3fb8aa3b, v41
	v_exp_f32_e32 v40, v40
	v_exp_f32_e32 v41, v41
	s_nop 0
	v_pk_add_f32 v[40:41], v[40:41], 1.0 op_sel_hi:[1,0] neg_lo:[1,0] neg_hi:[1,0]

; __device__ __forceinline__ unsigned cvt_pk_bf16(float lo, float hi) { unsigned r; asm volatile("v_cvt_pk_bf16_f32 %0, %1, %2" : "=v"(r) : "v"(lo), "v"(hi)); return r; }
;     __device__ __forceinline__ void operator()(const f32x4 (&acc)[2][2][4][2], const Unit& u, int wr, int wc, int fr, int fq) const {
;     ...
;             for (int m = 0; m < 4; ++m) { bf16_t* rowp = base + (size_t)(row0 + ai * HALF + m * 16) * ldc + col0;
; #pragma unroll
;                 for (int bj = 0; bj < 2; ++bj) { f32x4 v0 = acc[ai][bj][m][0], v1 = acc[ai][bj][m][1];
;                     if (ACT == 2) {
; #pragma unroll
;                         for (int e = 0; e < 4; ++e) { float a = fmaxf(v0[e], 0.f), b = fmaxf(v1[e], 0.f); v0[e] = a * a; v1[e] = b * b; } }
;                     if (ACT == 3) {
;                         v0 = v0 + *(const f32x4*)(zb + cb + bj * HALF); v1 = v1 + *(const f32x4*)(zb + cb + bj * HALF + 4);
;                         if (blk < 4) {
; #pragma unroll
;                             for (int e = 0; e < 4; ++e) { float s0 = 1.f / (1.f + __expf(-v0[e])), s1 = 1.f / (1.f + __expf(-v1[e]));
;                                 if (blk < 2) { s0 = 1.f - __expf(-0.60653066f * s0); s1 = 1.f - __expf(-0.60653066f * s1); }
;                                 v0[e] = s0; v1[e] = s1; } } }
;                     v0 = v0 * sc; v1 = v1 * sc; u32x4 w; w.x = cvt_pk_bf16(v0[0], v0[1]); w.y = cvt_pk_bf16(v0[2], v0[3]); w.z = cvt_pk_bf16(v1[0], v1[1]); w.w = cvt_pk_bf16(v1[2], v1[3]);
;                     *(u32x4*)(rowp + bj * HALF) = w; } }
.LBB0_673:
	v_add_u32_e32 v40, 0x90, v154
	v_mad_i64_i32 v[40:41], s[0:1], v40, s35, v[120:121]
	v_cvt_pk_bf16_f32 v44, v52, v53
	v_cvt_pk_bf16_f32 v45, v48, v49
	v_cvt_pk_bf16_f32 v46, v50, v51
	v_cvt_pk_bf16_f32 v47, v42, v43
	global_store_dwordx4 v[40:41], v[44:47], off
	s_nop 1
	v_mov_b32_e32 v44, v210
	v_mov_b32_e32 v45, v211
	v_mov_b32_e32 v46, v212
	v_mov_b32_e32 v47, v213
	s_nop 0
	v_mov_b32_e32 v48, v246
	v_mov_b32_e32 v49, v247
	v_mov_b32_e32 v50, v248
	v_mov_b32_e32 v51, v249
	s_and_b64 vcc, exec, s[42:43]
	v_pk_add_f32 v[42:43], v[34:35], v[46:47]
	v_pk_add_f32 v[46:47], v[32:33], v[44:45]
	v_pk_add_f32 v[34:35], v[38:39], v[50:51]
	v_pk_add_f32 v[44:45], v[36:37], v[48:49]
	s_cbranch_vccnz .LBB0_683
	v_mul_f32_e32 v32, 0xbfb8aa3b, v46
	v_mul_f32_e32 v33, 0xbfb8aa3b, v44
	v_exp_f32_e32 v32, v32
	v_exp_f32_e32 v33, v33
	s_nop 0
	v_pk_add_f32 v[32:33], v[32:33], 1.0 op_sel_hi:[1,0]
	s_nop 0
	v_div_scale_f32 v36, s[0:1], v33, v33, 1.0
	v_rcp_f32_e32 v37, v36
	s_nop 0
	v_fma_f32 v38, -v36, v37, 1.0
	v_fmac_f32_e32 v37, v38, v37
	v_div_scale_f32 v38, vcc, 1.0, v33, 1.0
	v_mul_f32_e32 v39, v38, v37
	v_fma_f32 v44, -v36, v39, v38
	v_fmac_f32_e32 v39, v44, v37
	v_fma_f32 v36, -v36, v39, v38
	v_div_fmas_f32 v36, v36, v37, v39
	v_div_fixup_f32 v33, v36, v33, 1.0
	v_div_scale_f32 v36, s[0:1], v32, v32, 1.0
	v_rcp_f32_e32 v37, v36
	s_nop 0
	v_fma_f32 v38, -v36, v37, 1.0
	v_fmac_f32_e32 v37, v38, v37
	v_div_scale_f32 v38, vcc, 1.0, v32, 1.0
	v_mul_f32_e32 v39, v38, v37
	v_fma_f32 v44, -v36, v39, v38
	v_fmac_f32_e32 v39, v44, v37
	v_fma_f32 v36, -v36, v39, v38
	v_div_fmas_f32 v36, v36, v37, v39
	v_div_fixup_f32 v32, v36, v32, 1.0
	s_and_b64 vcc, exec, s[40:41]
	s_cbranch_vccnz .LBB0_676
	v_mul_f32_e32 v32, 0xbf1b4598, v32
	v_mul_f32_e32 v33, 0xbf1b4598, v33
	v_mul_f32_e32 v32, 0x3fb8aa3b, v32
	v_mul_f32_e32 v33, 0x3fb8aa3b, v33
	v_exp_f32_e32 v32, v32
	v_exp_f32_e32 v33, v33
	s_nop 0
	v_pk_add_f32 v[32:33], v[32:33], 1.0 op_sel_hi:[1,0] neg_lo:[1,0] neg_hi:[1,0]

; __device__ __forceinline__ unsigned cvt_pk_bf16(float lo, float hi) { unsigned r; asm volatile("v_cvt_pk_bf16_f32 %0, %1, %2" : "=v"(r) : "v"(lo), "v"(hi)); return r; }
;     __device__ __forceinline__ void operator()(const f32x4 (&acc)[2][2][4][2], const Unit& u, int wr, int wc, int fr, int fq) const {
;     ...
;             for (int m = 0; m < 4; ++m) { bf16_t* rowp = base + (size_t)(row0 + ai * HALF + m * 16) * ldc + col0;
; #pragma unroll
;                 for (int bj = 0; bj < 2; ++bj) { f32x4 v0 = acc[ai][bj][m][0], v1 = acc[ai][bj][m][1];
;                     if (ACT == 2) {
; #pragma unroll
;                         for (int e = 0; e < 4; ++e) { float a = fmaxf(v0[e], 0.f), b = fmaxf(v1[e], 0.f); v0[e] = a * a; v1[e] = b * b; } }
;                     if (ACT == 3) {
;                         v0 = v0 + *(const f32x4*)(zb + cb + bj * HALF); v1 = v1 + *(const f32x4*)(zb + cb + bj * HALF + 4);
;                         if (blk < 4) {
; #pragma unroll
;                             for (int e = 0; e < 4; ++e) { float s0 = 1.f / (1.f + __expf(-v0[e])), s1 = 1.f / (1.f + __expf(-v1[e]));
;                                 if (blk < 2) { s0 = 1.f - __expf(-0.60653066f * s0); s1 = 1.f - __expf(-0.60653066f * s1); }
;                                 v0[e] = s0; v1[e] = s1; } } }
;                     v0 = v0 * sc; v1 = v1 * sc; u32x4 w; w.x = cvt_pk_bf16(v0[0], v0[1]); w.y = cvt_pk_bf16(v0[2], v0[3]); w.z = cvt_pk_bf16(v1[0], v1[1]); w.w = cvt_pk_bf16(v1[2], v1[3]);
;                     *(u32x4*)(rowp + bj * HALF) = w; } }
.LBB0_683:
	v_cvt_pk_bf16_f32 v36, v46, v47
	v_cvt_pk_bf16_f32 v37, v42, v43
	v_cvt_pk_bf16_f32 v38, v44, v45
	v_cvt_pk_bf16_f32 v39, v34, v35
	global_store_dwordx4 v[40:41], v[36:39], off offset:256
	s_nop 1
	v_mov_b32_e32 v34, v202
	v_mov_b32_e32 v35, v203
	v_mov_b32_e32 v36, v204
	v_mov_b32_e32 v37, v205
	s_nop 0
	v_mov_b32_e32 v38, v206
	v_mov_b32_e32 v39, v207
	v_mov_b32_e32 v40, v208
	v_mov_b32_e32 v41, v209
	s_and_b64 vcc, exec, s[42:43]
	v_pk_add_f32 v[32:33], v[26:27], v[36:37]
	v_pk_add_f32 v[36:37], v[24:25], v[34:35]
	v_pk_add_f32 v[26:27], v[30:31], v[40:41]
	v_pk_add_f32 v[34:35], v[28:29], v[38:39]
	s_cbranch_vccnz .LBB0_693
	v_mul_f32_e32 v24, 0xbfb8aa3b, v36
	v_mul_f32_e32 v25, 0xbfb8aa3b, v34
	v_exp_f32_e32 v24, v24
	v_exp_f32_e32 v25, v25
	s_nop 0
	v_pk_add_f32 v[24:25], v[24:25], 1.0 op_sel_hi:[1,0]
	s_nop 0
	v_div_scale_f32 v28, s[0:1], v25, v25, 1.0
	v_rcp_f32_e32 v29, v28
	s_nop 0
	v_fma_f32 v30, -v28, v29, 1.0
	v_fmac_f32_e32 v29, v30, v29
	v_div_scale_f32 v30, vcc, 1.0, v25, 1.0
	v_mul_f32_e32 v31, v30, v29
	v_fma_f32 v34, -v28, v31, v30
	v_fmac_f32_e32 v31, v34, v29
	v_fma_f32 v28, -v28, v31, v30
	v_div_fmas_f32 v28, v28, v29, v31
	v_div_fixup_f32 v25, v28, v25, 1.0
	v_div_scale_f32 v28, s[0:1], v24, v24, 1.0
	v_rcp_f32_e32 v29, v28
	s_nop 0
	v_fma_f32 v30, -v28, v29, 1.0
	v_fmac_f32_e32 v29, v30, v29
	v_div_scale_f32 v30, vcc, 1.0, v24, 1.0
	v_mul_f32_e32 v31, v30, v29
	v_fma_f32 v34, -v28, v31, v30
	v_fmac_f32_e32 v31, v34, v29
	v_fma_f32 v28, -v28, v31, v30
	v_div_fmas_f32 v28, v28, v29, v31
	v_div_fixup_f32 v24, v28, v24, 1.0
	s_and_b64 vcc, exec, s[40:41]
	s_cbranch_vccnz .LBB0_686
	v_mul_f32_e32 v24, 0xbf1b4598, v24
	v_mul_f32_e32 v25, 0xbf1b4598, v25
	v_mul_f32_e32 v24, 0x3fb8aa3b, v24
	v_mul_f32_e32 v25, 0x3fb8aa3b, v25
	v_exp_f32_e32 v24, v24
	v_exp_f32_e32 v25, v25
	s_nop 0
	v_pk_add_f32 v[24:25], v[24:25], 1.0 op_sel_hi:[1,0] neg_lo:[1,0] neg_hi:[1,0]

; __device__ __forceinline__ unsigned cvt_pk_bf16(float lo, float hi) { unsigned r; asm volatile("v_cvt_pk_bf16_f32 %0, %1, %2" : "=v"(r) : "v"(lo), "v"(hi)); return r; }
;     __device__ __forceinline__ void operator()(const f32x4 (&acc)[2][2][4][2], const Unit& u, int wr, int wc, int fr, int fq) const {
;     ...
;             for (int m = 0; m < 4; ++m) { bf16_t* rowp = base + (size_t)(row0 + ai * HALF + m * 16) * ldc + col0;
; #pragma unroll
;                 for (int bj = 0; bj < 2; ++bj) { f32x4 v0 = acc[ai][bj][m][0], v1 = acc[ai][bj][m][1];
;                     if (ACT == 2) {
; #pragma unroll
;                         for (int e = 0; e < 4; ++e) { float a = fmaxf(v0[e], 0.f), b = fmaxf(v1[e], 0.f); v0[e] = a * a; v1[e] = b * b; } }
;                     if (ACT == 3) {
;                         v0 = v0 + *(const f32x4*)(zb + cb + bj * HALF); v1 = v1 + *(const f32x4*)(zb + cb + bj * HALF + 4);
;                         if (blk < 4) {
; #pragma unroll
;                             for (int e = 0; e < 4; ++e) { float s0 = 1.f / (1.f + __expf(-v0[e])), s1 = 1.f / (1.f + __expf(-v1[e]));
;                                 if (blk < 2) { s0 = 1.f - __expf(-0.60653066f * s0); s1 = 1.f - __expf(-0.60653066f * s1); }
;                                 v0[e] = s0; v1[e] = s1; } } }
;                     v0 = v0 * sc; v1 = v1 * sc; u32x4 w; w.x = cvt_pk_bf16(v0[0], v0[1]); w.y = cvt_pk_bf16(v0[2], v0[3]); w.z = cvt_pk_bf16(v1[0], v1[1]); w.w = cvt_pk_bf16(v1[2], v1[3]);
;                     *(u32x4*)(rowp + bj * HALF) = w; } }
.LBB0_693:
	v_add_u32_e32 v24, 0xa0, v154
	v_mad_i64_i32 v[24:25], s[0:1], v24, s35, v[120:121]
	v_cvt_pk_bf16_f32 v28, v36, v37
	v_cvt_pk_bf16_f32 v29, v32, v33
	v_cvt_pk_bf16_f32 v30, v34, v35
	v_cvt_pk_bf16_f32 v31, v26, v27
	global_store_dwordx4 v[24:25], v[28:31], off
	s_nop 1
	v_mov_b32_e32 v28, v210
	v_mov_b32_e32 v29, v211
	v_mov_b32_e32 v30, v212
	v_mov_b32_e32 v31, v213
	s_nop 0
	v_mov_b32_e32 v32, v246
	v_mov_b32_e32 v33, v247
	v_mov_b32_e32 v34, v248
	v_mov_b32_e32 v35, v249
	s_and_b64 vcc, exec, s[42:43]
	v_pk_add_f32 v[26:27], v[18:19], v[30:31]
	v_pk_add_f32 v[30:31], v[16:17], v[28:29]
	v_pk_add_f32 v[18:19], v[22:23], v[34:35]
	v_pk_add_f32 v[28:29], v[20:21], v[32:33]
	s_cbranch_vccnz .LBB0_703
	v_mul_f32_e32 v16, 0xbfb8aa3b, v30
	v_mul_f32_e32 v17, 0xbfb8aa3b, v28
	v_exp_f32_e32 v16, v16
	v_exp_f32_e32 v17, v17
	s_nop 0
	v_pk_add_f32 v[16:17], v[16:17], 1.0 op_sel_hi:[1,0]
	s_nop 0
	v_div_scale_f32 v20, s[0:1], v17, v17, 1.0
	v_rcp_f32_e32 v21, v20
	s_nop 0
	v_fma_f32 v22, -v20, v21, 1.0
	v_fmac_f32_e32 v21, v22, v21
	v_div_scale_f32 v22, vcc, 1.0, v17, 1.0
	v_mul_f32_e32 v23, v22, v21
	v_fma_f32 v28, -v20, v23, v22
	v_fmac_f32_e32 v23, v28, v21
	v_fma_f32 v20, -v20, v23, v22
	v_div_fmas_f32 v20, v20, v21, v23
	v_div_fixup_f32 v17, v20, v17, 1.0
	v_div_scale_f32 v20, s[0:1], v16, v16, 1.0
	v_rcp_f32_e32 v21, v20
	s_nop 0
	v_fma_f32 v22, -v20, v21, 1.0
	v_fmac_f32_e32 v21, v22, v21
	v_div_scale_f32 v22, vcc, 1.0, v16, 1.0
	v_mul_f32_e32 v23, v22, v21
	v_fma_f32 v28, -v20, v23, v22
	v_fmac_f32_e32 v23, v28, v21
	v_fma_f32 v20, -v20, v23, v22
	v_div_fmas_f32 v20, v20, v21, v23
	v_div_fixup_f32 v16, v20, v16, 1.0
	s_and_b64 vcc, exec, s[40:41]
	s_cbranch_vccnz .LBB0_696
	v_mul_f32_e32 v16, 0xbf1b4598, v16
	v_mul_f32_e32 v17, 0xbf1b4598, v17
	v_mul_f32_e32 v16, 0x3fb8aa3b, v16
	v_mul_f32_e32 v17, 0x3fb8aa3b, v17
	v_exp_f32_e32 v16, v16
	v_exp_f32_e32 v17, v17
	s_nop 0
	v_pk_add_f32 v[16:17], v[16:17], 1.0 op_sel_hi:[1,0] neg_lo:[1,0] neg_hi:[1,0]

; __device__ __forceinline__ unsigned cvt_pk_bf16(float lo, float hi) { unsigned r; asm volatile("v_cvt_pk_bf16_f32 %0, %1, %2" : "=v"(r) : "v"(lo), "v"(hi)); return r; }
;     __device__ __forceinline__ void operator()(const f32x4 (&acc)[2][2][4][2], const Unit& u, int wr, int wc, int fr, int fq) const {
;     ...
;             for (int m = 0; m < 4; ++m) { bf16_t* rowp = base + (size_t)(row0 + ai * HALF + m * 16) * ldc + col0;
; #pragma unroll
;                 for (int bj = 0; bj < 2; ++bj) { f32x4 v0 = acc[ai][bj][m][0], v1 = acc[ai][bj][m][1];
;                     if (ACT == 2) {
; #pragma unroll
;                         for (int e = 0; e < 4; ++e) { float a = fmaxf(v0[e], 0.f), b = fmaxf(v1[e], 0.f); v0[e] = a * a; v1[e] = b * b; } }
;                     if (ACT == 3) {
;                         v0 = v0 + *(const f32x4*)(zb + cb + bj * HALF); v1 = v1 + *(const f32x4*)(zb + cb + bj * HALF + 4);
;                         if (blk < 4) {
; #pragma unroll
;                             for (int e = 0; e < 4; ++e) { float s0 = 1.f / (1.f + __expf(-v0[e])), s1 = 1.f / (1.f + __expf(-v1[e]));
;                                 if (blk < 2) { s0 = 1.f - __expf(-0.60653066f * s0); s1 = 1.f - __expf(-0.60653066f * s1); }
;                                 v0[e] = s0; v1[e] = s1; } } }
;                     v0 = v0 * sc; v1 = v1 * sc; u32x4 w; w.x = cvt_pk_bf16(v0[0], v0[1]); w.y = cvt_pk_bf16(v0[2], v0[3]); w.z = cvt_pk_bf16(v1[0], v1[1]); w.w = cvt_pk_bf16(v1[2], v1[3]);
;                     *(u32x4*)(rowp + bj * HALF) = w; } }
.LBB0_703:
	v_cvt_pk_bf16_f32 v20, v30, v31
	v_cvt_pk_bf16_f32 v21, v26, v27
	v_cvt_pk_bf16_f32 v22, v28, v29
	v_cvt_pk_bf16_f32 v23, v18, v19
	global_store_dwordx4 v[24:25], v[20:23], off offset:256
	s_nop 1
	v_mov_b32_e32 v18, v202
	v_mov_b32_e32 v19, v203
	v_mov_b32_e32 v20, v204
	v_mov_b32_e32 v21, v205
	s_nop 0
	v_mov_b32_e32 v22, v206
	v_mov_b32_e32 v23, v207
	v_mov_b32_e32 v24, v208
	v_mov_b32_e32 v25, v209
	s_and_b64 vcc, exec, s[42:43]
	v_pk_add_f32 v[16:17], v[10:11], v[20:21]
	v_pk_add_f32 v[20:21], v[8:9], v[18:19]
	v_pk_add_f32 v[10:11], v[14:15], v[24:25]
	v_pk_add_f32 v[18:19], v[12:13], v[22:23]
	s_cbranch_vccnz .LBB0_713
	v_mul_f32_e32 v8, 0xbfb8aa3b, v20
	v_mul_f32_e32 v9, 0xbfb8aa3b, v18
	v_exp_f32_e32 v8, v8
	v_exp_f32_e32 v9, v9
	s_nop 0
	v_pk_add_f32 v[8:9], v[8:9], 1.0 op_sel_hi:[1,0]
	s_nop 0
	v_div_scale_f32 v12, s[0:1], v9, v9, 1.0
	v_rcp_f32_e32 v13, v12
	s_nop 0
	v_fma_f32 v14, -v12, v13, 1.0
	v_fmac_f32_e32 v13, v14, v13
	v_div_scale_f32 v14, vcc, 1.0, v9, 1.0
	v_mul_f32_e32 v15, v14, v13
	v_fma_f32 v18, -v12, v15, v14
	v_fmac_f32_e32 v15, v18, v13
	v_fma_f32 v12, -v12, v15, v14
	v_div_fmas_f32 v12, v12, v13, v15
	v_div_fixup_f32 v9, v12, v9, 1.0
	v_div_scale_f32 v12, s[0:1], v8, v8, 1.0
	v_rcp_f32_e32 v13, v12
	s_nop 0
	v_fma_f32 v14, -v12, v13, 1.0
	v_fmac_f32_e32 v13, v14, v13
	v_div_scale_f32 v14, vcc, 1.0, v8, 1.0
	v_mul_f32_e32 v15, v14, v13
	v_fma_f32 v18, -v12, v15, v14
	v_fmac_f32_e32 v15, v18, v13
	v_fma_f32 v12, -v12, v15, v14
	v_div_fmas_f32 v12, v12, v13, v15
	v_div_fixup_f32 v8, v12, v8, 1.0
	s_and_b64 vcc, exec, s[40:41]
	s_cbranch_vccnz .LBB0_706
	v_mul_f32_e32 v8, 0xbf1b4598, v8
	v_mul_f32_e32 v9, 0xbf1b4598, v9
	v_mul_f32_e32 v8, 0x3fb8aa3b, v8
	v_mul_f32_e32 v9, 0x3fb8aa3b, v9
	v_exp_f32_e32 v8, v8
	v_exp_f32_e32 v9, v9
	s_nop 0
	v_pk_add_f32 v[8:9], v[8:9], 1.0 op_sel_hi:[1,0] neg_lo:[1,0] neg_hi:[1,0]

; __device__ __forceinline__ unsigned cvt_pk_bf16(float lo, float hi) { unsigned r; asm volatile("v_cvt_pk_bf16_f32 %0, %1, %2" : "=v"(r) : "v"(lo), "v"(hi)); return r; }
;     __device__ __forceinline__ void operator()(const f32x4 (&acc)[2][2][4][2], const Unit& u, int wr, int wc, int fr, int fq) const {
;     ...
;             for (int m = 0; m < 4; ++m) { bf16_t* rowp = base + (size_t)(row0 + ai * HALF + m * 16) * ldc + col0;
; #pragma unroll
;                 for (int bj = 0; bj < 2; ++bj) { f32x4 v0 = acc[ai][bj][m][0], v1 = acc[ai][bj][m][1];
;                     if (ACT == 2) {
; #pragma unroll
;                         for (int e = 0; e < 4; ++e) { float a = fmaxf(v0[e], 0.f), b = fmaxf(v1[e], 0.f); v0[e] = a * a; v1[e] = b * b; } }
;                     if (ACT == 3) {
;                         v0 = v0 + *(const f32x4*)(zb + cb + bj * HALF); v1 = v1 + *(const f32x4*)(zb + cb + bj * HALF + 4);
;                         if (blk < 4) {
; #pragma unroll
;                             for (int e = 0; e < 4; ++e) { float s0 = 1.f / (1.f + __expf(-v0[e])), s1 = 1.f / (1.f + __expf(-v1[e]));
;                                 if (blk < 2) { s0 = 1.f - __expf(-0.60653066f * s0); s1 = 1.f - __expf(-0.60653066f * s1); }
;                                 v0[e] = s0; v1[e] = s1; } } }
;                     v0 = v0 * sc; v1 = v1 * sc; u32x4 w; w.x = cvt_pk_bf16(v0[0], v0[1]); w.y = cvt_pk_bf16(v0[2], v0[3]); w.z = cvt_pk_bf16(v1[0], v1[1]); w.w = cvt_pk_bf16(v1[2], v1[3]);
;                     *(u32x4*)(rowp + bj * HALF) = w; } }
.LBB0_713:
	v_add_u32_e32 v8, 0xb0, v154
	v_mad_i64_i32 v[8:9], s[0:1], v8, s35, v[120:121]
	v_cvt_pk_bf16_f32 v12, v20, v21
	v_cvt_pk_bf16_f32 v13, v16, v17
	v_cvt_pk_bf16_f32 v14, v18, v19
	v_cvt_pk_bf16_f32 v15, v10, v11
	global_store_dwordx4 v[8:9], v[12:15], off
	s_nop 1
	v_mov_b32_e32 v12, v210
	v_mov_b32_e32 v13, v211
	v_mov_b32_e32 v14, v212
	v_mov_b32_e32 v15, v213
	s_nop 0
	v_mov_b32_e32 v16, v246
	v_mov_b32_e32 v17, v247
	v_mov_b32_e32 v18, v248
	v_mov_b32_e32 v19, v249
	s_and_b64 vcc, exec, s[42:43]
	v_pk_add_f32 v[10:11], v[2:3], v[14:15]
	v_pk_add_f32 v[14:15], v[0:1], v[12:13]
	v_pk_add_f32 v[2:3], v[6:7], v[18:19]
	v_pk_add_f32 v[12:13], v[4:5], v[16:17]
	s_cbranch_vccnz .LBB0_723
	v_mul_f32_e32 v0, 0xbfb8aa3b, v14
	v_mul_f32_e32 v1, 0xbfb8aa3b, v12
	v_exp_f32_e32 v0, v0
	v_exp_f32_e32 v1, v1
	s_nop 0
	v_pk_add_f32 v[0:1], v[0:1], 1.0 op_sel_hi:[1,0]
	s_nop 0
	v_div_scale_f32 v4, s[0:1], v1, v1, 1.0
	v_rcp_f32_e32 v5, v4
	s_nop 0
	v_fma_f32 v6, -v4, v5, 1.0
	v_fmac_f32_e32 v5, v6, v5
	v_div_scale_f32 v6, vcc, 1.0, v1, 1.0
	v_mul_f32_e32 v7, v6, v5
	v_fma_f32 v12, -v4, v7, v6
	v_fmac_f32_e32 v7, v12, v5
	v_fma_f32 v4, -v4, v7, v6
	v_div_fmas_f32 v4, v4, v5, v7
	v_div_fixup_f32 v1, v4, v1, 1.0
	v_div_scale_f32 v4, s[0:1], v0, v0, 1.0
	v_rcp_f32_e32 v5, v4
	s_nop 0
	v_fma_f32 v6, -v4, v5, 1.0
	v_fmac_f32_e32 v5, v6, v5
	v_div_scale_f32 v6, vcc, 1.0, v0, 1.0
	v_mul_f32_e32 v7, v6, v5
	v_fma_f32 v12, -v4, v7, v6
	v_fmac_f32_e32 v7, v12, v5
	v_fma_f32 v4, -v4, v7, v6
	v_div_fmas_f32 v4, v4, v5, v7
	v_div_fixup_f32 v0, v4, v0, 1.0
	s_and_b64 vcc, exec, s[40:41]
	s_cbranch_vccnz .LBB0_716
	v_mul_f32_e32 v0, 0xbf1b4598, v0
	v_mul_f32_e32 v1, 0xbf1b4598, v1
	v_mul_f32_e32 v0, 0x3fb8aa3b, v0
	v_mul_f32_e32 v1, 0x3fb8aa3b, v1
	v_exp_f32_e32 v0, v0
	v_exp_f32_e32 v1, v1
	s_nop 0
	v_pk_add_f32 v[0:1], v[0:1], 1.0 op_sel_hi:[1,0] neg_lo:[1,0] neg_hi:[1,0]
